# post_phase loops (x4): all row loads hoisted to the loop top with fresh registers, vmcnt re-derived
# speedup vs baseline: 1.0085x; 1.0085x over previous
.LBB0_902:
	s_or_b64 exec, exec, s[0:1]
	global_load_dwordx4 v[118:121], v[16:17], off
	global_load_dwordx4 v[130:133], v[16:17], off offset:1024
	global_load_dwordx4 v[142:145], v[16:17], off offset:2048
	global_load_dwordx4 v[154:157], v[16:17], off offset:3072
	global_load_dwordx4 v[166:169], v[14:15], off
	global_load_dwordx4 v[174:177], v[14:15], off offset:1024
	global_load_dwordx4 v[182:185], v[14:15], off offset:2048
	global_load_dwordx4 v[190:193], v[14:15], off offset:3072
	v_lshl_add_u64 v[50:51], v[0:1], 0, v[24:25]
	global_load_dwordx4 v[122:125], v[50:51], off
	global_load_dwordx4 v[134:137], v[50:51], off offset:1024
	global_load_dwordx4 v[146:149], v[50:51], off offset:2048
	global_load_dwordx4 v[158:161], v[50:51], off offset:3072
	v_lshlrev_b64 v[32:33], 11, v[8:9]
	v_lshl_add_u64 v[2:3], v[12:13], 0, v[32:33]
	global_load_dwordx2 v[110:111], v[2:3], off
	global_load_dwordx2 v[112:113], v[2:3], off offset:512
	global_load_dwordx2 v[114:115], v[2:3], off offset:1024
	global_load_dwordx2 v[116:117], v[2:3], off offset:1536
	v_lshrrev_b32_e32 v4, 11, v10
	v_mad_u32_u24 v10, v4, s15, s15
	s_nop 1
	v_cndmask_b32_e64 v10, v10, 0, vcc
	v_lshlrev_b64 v[54:55], 2, v[10:11]
	v_lshl_add_u64 v[52:53], v[18:19], 0, v[54:55]
	global_load_dwordx4 v[126:129], v[52:53], off
	global_load_dwordx4 v[138:141], v[52:53], off offset:1024
	global_load_dwordx4 v[150:153], v[52:53], off offset:2048
	global_load_dwordx4 v[162:165], v[52:53], off offset:3072
	v_lshl_add_u64 v[32:33], v[22:23], 0, v[32:33]
	s_waitcnt vmcnt(7)
	v_and_b32_e32 v57, 0xffff0000, v110
	s_waitcnt vmcnt(6)
	v_and_b32_e32 v59, 0xffff0000, v112
	v_lshlrev_b32_e32 v56, 16, v110
	v_lshlrev_b32_e32 v58, 16, v112
	s_waitcnt vmcnt(5)
	v_lshlrev_b32_e32 v62, 16, v114
	v_mov_b32_e32 v72, v62
	v_and_b32_e32 v63, 0xffff0000, v114
	v_mov_b32_e32 v74, v63
	v_lshlrev_b32_e32 v64, 16, v115
	v_and_b32_e32 v65, 0xffff0000, v115
	v_mov_b32_e32 v78, v65
	s_waitcnt vmcnt(4)
	v_and_b32_e32 v67, 0xffff0000, v116
	v_mov_b32_e32 v75, v67
	v_mov_b32_e32 v46, v57
	v_mov_b32_e32 v47, v59
	v_lshlrev_b32_e32 v42, 16, v111
	v_lshlrev_b32_e32 v60, 16, v113
	v_and_b32_e32 v61, 0xffff0000, v113
	v_lshlrev_b32_e32 v66, 16, v116
	v_mov_b32_e32 v73, v66
	v_mov_b32_e32 v44, v56
	v_mov_b32_e32 v45, v58
	v_pk_mul_f32 v[46:47], v[46:47], v[46:47]
	v_and_b32_e32 v43, 0xffff0000, v111
	v_lshlrev_b32_e32 v68, 16, v117
	v_and_b32_e32 v69, 0xffff0000, v117
	v_mov_b32_e32 v79, v69
	v_mov_b32_e32 v48, v42
	v_mov_b32_e32 v49, v60
	v_pk_mul_f32 v[74:75], v[74:75], v[74:75]
	v_pk_fma_f32 v[44:45], v[44:45], v[44:45], v[46:47]
	v_mov_b32_e32 v70, v43
	v_mov_b32_e32 v71, v61
	v_mov_b32_e32 v76, v64
	v_mov_b32_e32 v77, v68
	v_pk_fma_f32 v[46:47], v[72:73], v[72:73], v[74:75]
	v_pk_fma_f32 v[44:45], v[48:49], v[48:49], v[44:45]
	v_pk_fma_f32 v[46:47], v[76:77], v[76:77], v[46:47]
	v_pk_fma_f32 v[44:45], v[70:71], v[70:71], v[44:45]
	v_pk_fma_f32 v[46:47], v[78:79], v[78:79], v[46:47]
	v_lshl_add_u64 v[78:79], s[6:7], 0, v[54:55]
	v_lshl_add_u64 v[90:91], v[78:79], 0, v[24:25]
	global_load_dwordx4 v[202:205], v[90:91], off
	global_load_dwordx4 v[206:209], v[90:91], off offset:1024
	global_load_dwordx4 v[210:213], v[90:91], off offset:2048
	global_load_dwordx4 v[214:217], v[90:91], off offset:3072
	v_lshl_add_u64 v[72:73], v[78:79], 0, s[10:11]
	v_lshl_add_u64 v[74:75], v[72:73], 0, v[30:31]
	global_load_dwordx4 v[198:201], v[74:75], off
	v_lshl_add_u64 v[54:55], v[72:73], 0, v[24:25]
	global_load_dwordx4 v[170:173], v[54:55], off
	v_add_f32_e32 v10, v44, v45
	v_add_f32_e32 v10, v10, v46
	v_add_f32_e32 v10, v10, v47
	v_lshlrev_b64 v[44:45], 12, v[8:9]
	v_lshl_add_u64 v[70:71], v[20:21], 0, v[44:45]
	s_nop 1
	v_add_f32_dpp v10, v10, v10 quad_perm:[1,0,3,2] row_mask:0xf bank_mask:0xf bound_ctrl:1
	s_nop 1
	v_add_f32_dpp v10, v10, v10 quad_perm:[2,3,0,1] row_mask:0xf bank_mask:0xf bound_ctrl:1
	s_nop 1
	v_add_f32_dpp v10, v10, v10 row_half_mirror row_mask:0xf bank_mask:0xf bound_ctrl:1
	v_add_u32_e32 v8, s12, v8
	s_nop 1
	v_add_f32_dpp v10, v10, v10 row_mirror row_mask:0xf bank_mask:0xf bound_ctrl:1
	s_nop 1
	ds_bpermute_b32 v37, v34, v10
	v_cmp_lt_i32_e64 s[0:1], s17, v8
	s_or_b64 s[8:9], s[0:1], s[8:9]
	s_waitcnt lgkmcnt(0)
	v_add_f32_e32 v10, v10, v37
	s_nop 1
	ds_bpermute_b32 v37, v35, v10
	s_waitcnt lgkmcnt(0)
	v_add_f32_e32 v10, v10, v37
	v_fmamk_f32 v10, v10, 0x3a800000, v36
	v_mul_f32_e32 v37, 0x4b800000, v10
	v_cmp_gt_f32_e32 vcc, s16, v10
	s_nop 1
	s_nop 1
	v_cndmask_b32_e32 v10, v10, v37, vcc
	v_rsq_f32_e32 v10, v10
	s_nop 0
	s_nop 0
	v_mul_f32_e32 v9, 0x45800000, v10
	s_nop 1
	v_cndmask_b32_e32 v10, v10, v9, vcc
	v_pk_mul_f32 v[44:45], v[10:11], v[56:57] op_sel_hi:[0,1]
	v_pk_mul_f32 v[42:43], v[10:11], v[42:43] op_sel_hi:[0,1]
	v_pk_mul_f32 v[0:1], v[118:119], v[44:45]
	v_pk_mul_f32 v[2:3], v[120:121], v[42:43]
	s_waitcnt vmcnt(9)
	v_pk_fma_f32 v[0:1], v[126:127], v[0:1], v[122:123]
	v_pk_fma_f32 v[2:3], v[128:129], v[2:3], v[124:125]
	global_store_dwordx4 v[70:71], v[0:3], off
	s_nop 1
	v_pk_mul_f32 v[46:47], v[10:11], v[58:59] op_sel_hi:[0,1]
	v_pk_mul_f32 v[48:49], v[10:11], v[60:61] op_sel_hi:[0,1]
	v_pk_mul_f32 v[56:57], v[10:11], v[62:63] op_sel_hi:[0,1]
	v_pk_mul_f32 v[58:59], v[10:11], v[64:65] op_sel_hi:[0,1]
	v_mov_b32_e32 v96, v1
	v_mov_b32_e32 v94, v0
	v_mov_b32_e32 v98, v2
	v_mov_b32_e32 v100, v3
	v_pk_mul_f32 v[4:5], v[46:47], v[130:131]
	v_pk_mul_f32 v[6:7], v[48:49], v[132:133]
	s_waitcnt vmcnt(9)
	v_pk_fma_f32 v[4:5], v[4:5], v[138:139], v[134:135]
	v_pk_fma_f32 v[6:7], v[6:7], v[140:141], v[136:137]
	global_store_dwordx4 v[70:71], v[4:7], off offset:1024
	s_nop 1
	v_mov_b32_e32 v97, v5
	v_mov_b32_e32 v95, v4
	v_pk_mul_f32 v[96:97], v[96:97], v[96:97]
	v_mov_b32_e32 v99, v6
	v_pk_fma_f32 v[94:95], v[94:95], v[94:95], v[96:97]
	v_mov_b32_e32 v101, v7
	v_pk_fma_f32 v[94:95], v[98:99], v[98:99], v[94:95]
	v_pk_mul_f32 v[38:39], v[56:57], v[142:143]
	v_pk_mul_f32 v[40:41], v[58:59], v[144:145]
	s_waitcnt vmcnt(9)
	v_pk_fma_f32 v[38:39], v[38:39], v[150:151], v[146:147]
	v_pk_fma_f32 v[40:41], v[40:41], v[152:153], v[148:149]
	global_store_dwordx4 v[70:71], v[38:41], off offset:2048
	s_nop 1
	s_nop 0
	v_pk_mul_f32 v[56:57], v[10:11], v[66:67] op_sel_hi:[0,1]
	v_lshl_add_u64 v[66:67], v[72:73], 0, v[28:29]
	global_load_dwordx4 v[186:189], v[66:67], off
	v_pk_mul_f32 v[58:59], v[10:11], v[68:69] op_sel_hi:[0,1]
	v_pk_fma_f32 v[94:95], v[100:101], v[100:101], v[94:95]
	v_mov_b32_e32 v96, v39
	v_add_f32_e32 v9, v94, v95
	v_mov_b32_e32 v94, v38
	v_mov_b32_e32 v98, v40
	v_mov_b32_e32 v100, v41
	v_pk_mul_f32 v[42:43], v[56:57], v[154:155]
	v_pk_mul_f32 v[44:45], v[58:59], v[156:157]
	v_lshl_add_u64 v[58:59], v[72:73], 0, v[26:27]
	global_load_dwordx4 v[178:181], v[58:59], off
	s_waitcnt vmcnt(11)
	v_pk_fma_f32 v[42:43], v[42:43], v[162:163], v[158:159]
	v_pk_fma_f32 v[44:45], v[44:45], v[164:165], v[160:161]
	global_store_dwordx4 v[70:71], v[42:45], off offset:3072
	s_nop 1
	s_nop 0
	s_nop 0
	s_nop 0
	s_nop 0
	s_nop 0
	v_mov_b32_e32 v97, v43
	v_mov_b32_e32 v95, v42
	v_pk_mul_f32 v[96:97], v[96:97], v[96:97]
	v_mov_b32_e32 v99, v44
	v_pk_fma_f32 v[94:95], v[94:95], v[94:95], v[96:97]
	v_mov_b32_e32 v101, v45
	v_pk_fma_f32 v[94:95], v[98:99], v[98:99], v[94:95]
	s_nop 0
	v_pk_fma_f32 v[94:95], v[100:101], v[100:101], v[94:95]
	s_nop 0
	v_add_f32_e32 v9, v9, v94
	v_add_f32_e32 v9, v9, v95
	s_nop 1
	s_nop 1
	v_add_f32_dpp v9, v9, v9 quad_perm:[1,0,3,2] row_mask:0xf bank_mask:0xf bound_ctrl:1
	s_nop 1
	s_nop 1
	v_add_f32_dpp v9, v9, v9 quad_perm:[2,3,0,1] row_mask:0xf bank_mask:0xf bound_ctrl:1
	s_nop 1
	s_nop 1
	v_add_f32_dpp v9, v9, v9 row_half_mirror row_mask:0xf bank_mask:0xf bound_ctrl:1
	s_nop 1
	s_nop 1
	v_add_f32_dpp v9, v9, v9 row_mirror row_mask:0xf bank_mask:0xf bound_ctrl:1
	s_nop 1
	ds_bpermute_b32 v10, v34, v9
	s_waitcnt lgkmcnt(0)
	v_add_f32_e32 v9, v9, v10
	s_nop 1
	ds_bpermute_b32 v10, v35, v9
	s_waitcnt lgkmcnt(0)
	v_add_f32_e32 v9, v9, v10
	v_fmamk_f32 v9, v9, 0x3a800000, v36
	v_mul_f32_e32 v10, 0x4b800000, v9
	v_cmp_gt_f32_e32 vcc, s16, v9
	s_nop 1
	s_nop 1
	v_cndmask_b32_e32 v9, v9, v10, vcc
	v_rsq_f32_e32 v9, v9
	s_nop 0
	s_nop 0
	v_mul_f32_e32 v10, 0x45800000, v9
	s_nop 1
	v_cndmask_b32_e32 v10, v9, v10, vcc
	v_pk_mul_f32 v[0:1], v[0:1], v[10:11] op_sel_hi:[1,0]
	v_pk_mul_f32 v[2:3], v[2:3], v[10:11] op_sel_hi:[1,0]
	v_pk_mul_f32 v[4:5], v[4:5], v[10:11] op_sel_hi:[1,0]
	v_pk_mul_f32 v[6:7], v[6:7], v[10:11] op_sel_hi:[1,0]
	v_pk_mul_f32 v[38:39], v[38:39], v[10:11] op_sel_hi:[1,0]
	v_pk_mul_f32 v[40:41], v[40:41], v[10:11] op_sel_hi:[1,0]
	v_pk_mul_f32 v[42:43], v[42:43], v[10:11] op_sel_hi:[1,0]
	v_pk_mul_f32 v[44:45], v[44:45], v[10:11] op_sel_hi:[1,0]
	v_pk_mul_f32 v[0:1], v[166:167], v[0:1]
	s_waitcnt vmcnt(6)
	v_pk_add_f32 v[46:47], v[170:171], 1.0 op_sel_hi:[1,0]
	v_pk_mul_f32 v[2:3], v[168:169], v[2:3]
	v_pk_add_f32 v[48:49], v[172:173], 1.0 op_sel_hi:[1,0]
	v_pk_mul_f32 v[4:5], v[4:5], v[174:175]
	s_waitcnt vmcnt(1)
	v_pk_add_f32 v[50:51], v[178:179], 1.0 op_sel_hi:[1,0]
	v_pk_mul_f32 v[6:7], v[6:7], v[176:177]
	v_pk_add_f32 v[52:53], v[180:181], 1.0 op_sel_hi:[1,0]
	v_pk_mul_f32 v[38:39], v[38:39], v[182:183]
	v_pk_add_f32 v[54:55], v[186:187], 1.0 op_sel_hi:[1,0]
	v_pk_mul_f32 v[40:41], v[40:41], v[184:185]
	v_pk_add_f32 v[56:57], v[188:189], 1.0 op_sel_hi:[1,0]
	v_pk_mul_f32 v[42:43], v[42:43], v[190:191]
	v_pk_add_f32 v[58:59], v[198:199], 1.0 op_sel_hi:[1,0]
	v_pk_mul_f32 v[44:45], v[44:45], v[192:193]
	v_pk_add_f32 v[60:61], v[200:201], 1.0 op_sel_hi:[1,0]
	v_pk_fma_f32 v[0:1], v[0:1], v[46:47], v[202:203]
	v_pk_fma_f32 v[2:3], v[2:3], v[48:49], v[204:205]
	v_pk_fma_f32 v[4:5], v[4:5], v[50:51], v[206:207]
	v_pk_fma_f32 v[6:7], v[6:7], v[52:53], v[208:209]
	v_pk_fma_f32 v[38:39], v[38:39], v[54:55], v[210:211]
	v_pk_fma_f32 v[40:41], v[40:41], v[56:57], v[212:213]
	v_pk_fma_f32 v[42:43], v[42:43], v[58:59], v[214:215]
	v_pk_fma_f32 v[44:45], v[44:45], v[60:61], v[216:217]
	v_cvt_pk_bf16_f32 v0, v0, v1
	v_cvt_pk_bf16_f32 v1, v2, v3
	v_cvt_pk_bf16_f32 v2, v4, v5
	v_cvt_pk_bf16_f32 v3, v6, v7
	v_cvt_pk_bf16_f32 v4, v38, v39
	v_cvt_pk_bf16_f32 v5, v40, v41
	v_cvt_pk_bf16_f32 v6, v42, v43
	v_cvt_pk_bf16_f32 v7, v44, v45
	global_store_dwordx2 v[32:33], v[0:1], off
	s_nop 1
	global_store_dwordx2 v[32:33], v[2:3], off offset:512
	s_nop 1
	global_store_dwordx2 v[32:33], v[4:5], off offset:1024
	s_nop 1
	global_store_dwordx2 v[32:33], v[6:7], off offset:1536
	s_nop 1
	s_andn2_b64 exec, exec, s[8:9]
	s_cbranch_execz .LBB0_907

.LBB0_1178:
	global_load_dwordx4 v[110:113], v[20:21], off
	global_load_dwordx4 v[134:137], v[20:21], off offset:1024
	global_load_dwordx4 v[146:149], v[20:21], off offset:2048
	global_load_dwordx4 v[158:161], v[20:21], off offset:3072
	global_load_dwordx4 v[166:169], v[18:19], off
	global_load_dwordx4 v[174:177], v[18:19], off offset:1024
	global_load_dwordx4 v[182:185], v[18:19], off offset:2048
	global_load_dwordx4 v[190:193], v[18:19], off offset:3072
	v_ashrrev_i32_e32 v13, 31, v12
	v_lshlrev_b64 v[42:43], 11, v[12:13]
	v_add_u32_e32 v4, 0xffffe000, v12
	v_ashrrev_i32_e32 v6, 11, v4
	v_lshlrev_b64 v[4:5], 12, v[12:13]
	v_lshl_add_u64 v[34:35], v[22:23], 0, v[4:5]
	global_load_dwordx4 v[122:125], v[34:35], off
	global_load_dwordx4 v[126:129], v[34:35], off offset:1024
	global_load_dwordx4 v[142:145], v[34:35], off offset:2048
	global_load_dwordx4 v[154:157], v[34:35], off offset:3072
	v_mad_i32_i24 v8, v6, s9, s9
	v_lshl_add_u64 v[6:7], v[16:17], 0, v[42:43]
	global_load_dwordx2 v[114:115], v[6:7], off
	global_load_dwordx2 v[116:117], v[6:7], off offset:512
	global_load_dwordx2 v[118:119], v[6:7], off offset:1024
	global_load_dwordx2 v[120:121], v[6:7], off offset:1536
	v_cmp_lt_i32_e32 vcc, s10, v12
	s_nop 1
	v_cndmask_b32_e32 v36, 0, v8, vcc
	v_ashrrev_i32_e32 v37, 31, v36
	v_lshl_add_u64 v[60:61], v[36:37], 2, v[24:25]
	global_load_dwordx4 v[130:133], v[60:61], off
	global_load_dwordx4 v[138:141], v[60:61], off offset:1024
	global_load_dwordx4 v[150:153], v[60:61], off offset:2048
	global_load_dwordx4 v[162:165], v[60:61], off offset:3072
	v_add_u32_e32 v36, 0x4800, v36
	v_lshl_add_u64 v[92:93], v[26:27], 0, v[42:43]
	v_add_u32_e32 v12, s8, v12
	s_waitcnt vmcnt(7)
	v_and_b32_e32 v57, 0xffff0000, v114
	s_waitcnt vmcnt(6)
	v_and_b32_e32 v63, 0xffff0000, v116
	v_lshlrev_b32_e32 v56, 16, v114
	v_lshlrev_b32_e32 v58, 16, v115
	v_and_b32_e32 v59, 0xffff0000, v115
	v_lshlrev_b32_e32 v62, 16, v116
	v_lshlrev_b32_e32 v64, 16, v117
	v_and_b32_e32 v65, 0xffff0000, v117
	s_waitcnt vmcnt(5)
	v_and_b32_e32 v67, 0xffff0000, v118
	s_waitcnt vmcnt(4)
	v_lshlrev_b32_e32 v38, 16, v120
	v_and_b32_e32 v39, 0xffff0000, v120
	v_lshlrev_b32_e32 v40, 16, v121
	v_and_b32_e32 v41, 0xffff0000, v121
	v_mov_b32_e32 v54, v57
	v_mov_b32_e32 v55, v63
	v_lshlrev_b32_e32 v66, 16, v118
	v_lshlrev_b32_e32 v68, 16, v119
	v_and_b32_e32 v69, 0xffff0000, v119
	v_mov_b32_e32 v52, v56
	v_mov_b32_e32 v53, v62
	v_mov_b32_e32 v76, v67
	v_mov_b32_e32 v77, v39
	v_pk_mul_f32 v[54:55], v[54:55], v[54:55]
	v_mov_b32_e32 v70, v58
	v_mov_b32_e32 v71, v64
	v_mov_b32_e32 v74, v66
	v_mov_b32_e32 v75, v38
	v_pk_mul_f32 v[76:77], v[76:77], v[76:77]
	v_pk_fma_f32 v[52:53], v[52:53], v[52:53], v[54:55]
	v_mov_b32_e32 v72, v59
	v_mov_b32_e32 v73, v65
	v_mov_b32_e32 v78, v68
	v_mov_b32_e32 v79, v40
	v_pk_fma_f32 v[54:55], v[74:75], v[74:75], v[76:77]
	v_pk_fma_f32 v[52:53], v[70:71], v[70:71], v[52:53]
	v_mov_b32_e32 v80, v69
	v_mov_b32_e32 v81, v41
	v_pk_fma_f32 v[54:55], v[78:79], v[78:79], v[54:55]
	v_pk_fma_f32 v[52:53], v[72:73], v[72:73], v[52:53]
	v_pk_fma_f32 v[54:55], v[80:81], v[80:81], v[54:55]
	v_add_f32_e32 v13, v52, v53
	v_add_f32_e32 v13, v13, v54
	v_add_f32_e32 v13, v13, v55
	s_nop 1
	s_nop 1
	v_add_f32_dpp v13, v13, v13 quad_perm:[1,0,3,2] row_mask:0xf bank_mask:0xf bound_ctrl:1
	s_nop 1
	s_nop 1
	v_add_f32_dpp v13, v13, v13 quad_perm:[2,3,0,1] row_mask:0xf bank_mask:0xf bound_ctrl:1
	s_nop 1
	s_nop 1
	v_add_f32_dpp v13, v13, v13 row_half_mirror row_mask:0xf bank_mask:0xf bound_ctrl:1
	s_nop 1
	s_nop 1
	v_add_f32_dpp v13, v13, v13 row_mirror row_mask:0xf bank_mask:0xf bound_ctrl:1
	s_nop 1
	ds_bpermute_b32 v37, v44, v13
	s_waitcnt lgkmcnt(0)
	v_add_f32_e32 v13, v13, v37
	s_nop 1
	ds_bpermute_b32 v37, v45, v13
	s_waitcnt lgkmcnt(0)
	v_add_f32_e32 v13, v13, v37
	v_fmamk_f32 v13, v13, 0x3a800000, v46
	v_mul_f32_e32 v37, 0x4b800000, v13
	v_cmp_gt_f32_e32 vcc, s11, v13
	s_nop 1
	s_nop 1
	v_cndmask_b32_e32 v13, v13, v37, vcc
	v_rsq_f32_e32 v13, v13
	s_nop 0
	s_nop 0
	v_mul_f32_e32 v37, 0x45800000, v13
	s_nop 1
	v_cndmask_b32_e32 v70, v13, v37, vcc
	v_ashrrev_i32_e32 v37, 31, v36
	v_lshl_add_u64 v[36:37], v[36:37], 2, s[88:89]
	v_lshl_add_u64 v[94:95], v[36:37], 0, v[14:15]
	global_load_dwordx4 v[202:205], v[94:95], off
	global_load_dwordx4 v[206:209], v[94:95], off offset:1024
	global_load_dwordx4 v[210:213], v[94:95], off offset:2048
	global_load_dwordx4 v[214:217], v[94:95], off offset:3072
	v_lshl_add_u64 v[42:43], v[36:37], 0, s[6:7]
	v_lshl_add_u64 v[102:103], v[42:43], 0, v[32:33]
	global_load_dwordx4 v[198:201], v[102:103], off
	v_lshl_add_u64 v[100:101], v[42:43], 0, v[30:31]
	global_load_dwordx4 v[186:189], v[100:101], off
	v_lshl_add_u64 v[98:99], v[42:43], 0, v[28:29]
	global_load_dwordx4 v[178:181], v[98:99], off
	v_lshl_add_u64 v[96:97], v[42:43], 0, v[14:15]
	global_load_dwordx4 v[170:173], v[96:97], off
	v_pk_mul_f32 v[52:53], v[70:71], v[56:57] op_sel_hi:[0,1]
	v_pk_mul_f32 v[54:55], v[70:71], v[58:59] op_sel_hi:[0,1]
	v_pk_mul_f32 v[0:1], v[110:111], v[52:53]
	v_pk_mul_f32 v[2:3], v[112:113], v[54:55]
	s_waitcnt vmcnt(11)
	v_pk_fma_f32 v[0:1], v[130:131], v[0:1], v[122:123]
	v_pk_fma_f32 v[2:3], v[132:133], v[2:3], v[124:125]
	global_store_dwordx4 v[34:35], v[0:3], off
	s_nop 1
	v_pk_mul_f32 v[56:57], v[70:71], v[62:63] op_sel_hi:[0,1]
	v_pk_mul_f32 v[58:59], v[70:71], v[64:65] op_sel_hi:[0,1]
	v_pk_mul_f32 v[62:63], v[70:71], v[66:67] op_sel_hi:[0,1]
	v_pk_mul_f32 v[64:65], v[70:71], v[68:69] op_sel_hi:[0,1]
	v_mov_b32_e32 v42, v1
	v_pk_mul_f32 v[36:37], v[70:71], v[38:39] op_sel_hi:[0,1]
	v_pk_mul_f32 v[38:39], v[70:71], v[40:41] op_sel_hi:[0,1]
	v_mov_b32_e32 v40, v0
	v_cmp_lt_i32_e32 vcc, s12, v12
	s_or_b64 s[4:5], vcc, s[4:5]
	v_pk_mul_f32 v[4:5], v[56:57], v[134:135]
	v_pk_mul_f32 v[6:7], v[58:59], v[136:137]
	s_waitcnt vmcnt(11)
	v_pk_fma_f32 v[4:5], v[4:5], v[138:139], v[126:127]
	v_pk_fma_f32 v[6:7], v[6:7], v[140:141], v[128:129]
	global_store_dwordx4 v[34:35], v[4:7], off offset:1024
	s_nop 1
	v_mov_b32_e32 v43, v5
	v_mov_b32_e32 v41, v4
	v_pk_mul_f32 v[42:43], v[42:43], v[42:43]
	v_pk_mul_f32 v[8:9], v[62:63], v[146:147]
	v_pk_mul_f32 v[10:11], v[64:65], v[148:149]
	s_waitcnt vmcnt(11)
	v_pk_fma_f32 v[8:9], v[8:9], v[150:151], v[142:143]
	v_pk_fma_f32 v[10:11], v[10:11], v[152:153], v[144:145]
	global_store_dwordx4 v[34:35], v[8:11], off offset:2048
	s_nop 1
	v_mov_b32_e32 v60, v2
	v_mov_b32_e32 v61, v6
	v_pk_fma_f32 v[40:41], v[40:41], v[40:41], v[42:43]
	v_mov_b32_e32 v62, v3
	v_mov_b32_e32 v63, v7
	v_pk_fma_f32 v[40:41], v[60:61], v[60:61], v[40:41]
	v_mov_b32_e32 v106, v9
	v_pk_fma_f32 v[40:41], v[62:63], v[62:63], v[40:41]
	v_mov_b32_e32 v104, v8
	v_add_f32_e32 v13, v40, v41
	v_pk_mul_f32 v[36:37], v[36:37], v[158:159]
	v_pk_mul_f32 v[38:39], v[38:39], v[160:161]
	s_waitcnt vmcnt(11)
	v_pk_fma_f32 v[36:37], v[36:37], v[162:163], v[154:155]
	v_pk_fma_f32 v[38:39], v[38:39], v[164:165], v[156:157]
	global_store_dwordx4 v[34:35], v[36:39], off offset:3072
	s_nop 1
	v_mov_b32_e32 v107, v37
	v_mov_b32_e32 v105, v36
	v_pk_mul_f32 v[96:97], v[106:107], v[106:107]
	v_mov_b32_e32 v34, v10
	v_mov_b32_e32 v35, v38
	v_pk_fma_f32 v[96:97], v[104:105], v[104:105], v[96:97]
	v_mov_b32_e32 v94, v11
	v_mov_b32_e32 v95, v39
	v_pk_fma_f32 v[34:35], v[34:35], v[34:35], v[96:97]
	s_nop 0
	v_pk_fma_f32 v[34:35], v[94:95], v[94:95], v[34:35]
	s_nop 0
	v_add_f32_e32 v13, v13, v34
	v_add_f32_e32 v13, v13, v35
	s_nop 1
	s_nop 1
	v_add_f32_dpp v13, v13, v13 quad_perm:[1,0,3,2] row_mask:0xf bank_mask:0xf bound_ctrl:1
	s_nop 1
	s_nop 1
	v_add_f32_dpp v13, v13, v13 quad_perm:[2,3,0,1] row_mask:0xf bank_mask:0xf bound_ctrl:1
	s_nop 1
	s_nop 1
	v_add_f32_dpp v13, v13, v13 row_half_mirror row_mask:0xf bank_mask:0xf bound_ctrl:1
	s_nop 1
	s_nop 1
	v_add_f32_dpp v13, v13, v13 row_mirror row_mask:0xf bank_mask:0xf bound_ctrl:1
	s_nop 1
	ds_bpermute_b32 v34, v44, v13
	s_waitcnt lgkmcnt(0)
	v_add_f32_e32 v13, v13, v34
	s_nop 1
	ds_bpermute_b32 v34, v45, v13
	s_waitcnt lgkmcnt(0)
	v_add_f32_e32 v13, v13, v34
	v_fmamk_f32 v13, v13, 0x3a800000, v46
	v_mul_f32_e32 v34, 0x4b800000, v13
	v_cmp_gt_f32_e32 vcc, s11, v13
	s_nop 1
	s_nop 1
	v_cndmask_b32_e32 v13, v13, v34, vcc
	v_rsq_f32_e32 v13, v13
	s_nop 0
	s_nop 0
	v_mul_f32_e32 v34, 0x45800000, v13
	s_nop 1
	v_cndmask_b32_e32 v34, v13, v34, vcc
	v_pk_mul_f32 v[0:1], v[0:1], v[34:35] op_sel_hi:[1,0]
	v_pk_mul_f32 v[2:3], v[2:3], v[34:35] op_sel_hi:[1,0]
	v_pk_mul_f32 v[4:5], v[4:5], v[34:35] op_sel_hi:[1,0]
	v_pk_mul_f32 v[6:7], v[6:7], v[34:35] op_sel_hi:[1,0]
	v_pk_mul_f32 v[8:9], v[8:9], v[34:35] op_sel_hi:[1,0]
	v_pk_mul_f32 v[10:11], v[10:11], v[34:35] op_sel_hi:[1,0]
	v_pk_mul_f32 v[36:37], v[36:37], v[34:35] op_sel_hi:[1,0]
	v_pk_mul_f32 v[34:35], v[38:39], v[34:35] op_sel_hi:[1,0]
	v_pk_mul_f32 v[0:1], v[166:167], v[0:1]
	s_waitcnt vmcnt(4)
	v_pk_add_f32 v[38:39], v[170:171], 1.0 op_sel_hi:[1,0]
	v_pk_mul_f32 v[2:3], v[168:169], v[2:3]
	v_pk_add_f32 v[40:41], v[172:173], 1.0 op_sel_hi:[1,0]
	v_pk_mul_f32 v[4:5], v[4:5], v[174:175]
	v_pk_add_f32 v[42:43], v[178:179], 1.0 op_sel_hi:[1,0]
	v_pk_mul_f32 v[6:7], v[6:7], v[176:177]
	v_pk_add_f32 v[48:49], v[180:181], 1.0 op_sel_hi:[1,0]
	v_pk_mul_f32 v[8:9], v[8:9], v[182:183]
	v_pk_add_f32 v[50:51], v[186:187], 1.0 op_sel_hi:[1,0]
	v_pk_mul_f32 v[10:11], v[10:11], v[184:185]
	v_pk_add_f32 v[52:53], v[188:189], 1.0 op_sel_hi:[1,0]
	v_pk_mul_f32 v[36:37], v[36:37], v[190:191]
	v_pk_add_f32 v[54:55], v[198:199], 1.0 op_sel_hi:[1,0]
	v_pk_mul_f32 v[34:35], v[34:35], v[192:193]
	v_pk_add_f32 v[56:57], v[200:201], 1.0 op_sel_hi:[1,0]
	v_pk_fma_f32 v[0:1], v[0:1], v[38:39], v[202:203]
	v_pk_fma_f32 v[2:3], v[2:3], v[40:41], v[204:205]
	v_pk_fma_f32 v[4:5], v[4:5], v[42:43], v[206:207]
	v_pk_fma_f32 v[6:7], v[6:7], v[48:49], v[208:209]
	v_pk_fma_f32 v[8:9], v[8:9], v[50:51], v[210:211]
	v_pk_fma_f32 v[10:11], v[10:11], v[52:53], v[212:213]
	v_pk_fma_f32 v[36:37], v[36:37], v[54:55], v[214:215]
	v_pk_fma_f32 v[34:35], v[34:35], v[56:57], v[216:217]
	v_cvt_pk_bf16_f32 v0, v0, v1
	v_cvt_pk_bf16_f32 v1, v2, v3
	v_cvt_pk_bf16_f32 v2, v4, v5
	v_cvt_pk_bf16_f32 v3, v6, v7
	v_cvt_pk_bf16_f32 v4, v8, v9
	v_cvt_pk_bf16_f32 v5, v10, v11
	v_cvt_pk_bf16_f32 v6, v36, v37
	v_cvt_pk_bf16_f32 v7, v34, v35
	global_store_dwordx2 v[92:93], v[0:1], off
	s_nop 1
	global_store_dwordx2 v[92:93], v[2:3], off offset:512
	s_nop 1
	global_store_dwordx2 v[92:93], v[4:5], off offset:1024
	s_nop 1
	global_store_dwordx2 v[92:93], v[6:7], off offset:1536
	s_nop 1
	s_andn2_b64 exec, exec, s[4:5]
	s_cbranch_execnz .LBB0_1178

.LBB0_1834:
	global_load_dwordx4 v[110:113], v[16:17], off
	global_load_dwordx4 v[134:137], v[16:17], off offset:1024
	global_load_dwordx4 v[146:149], v[16:17], off offset:2048
	global_load_dwordx4 v[158:161], v[16:17], off offset:3072
	global_load_dwordx4 v[166:169], v[14:15], off
	global_load_dwordx4 v[174:177], v[14:15], off offset:1024
	global_load_dwordx4 v[182:185], v[14:15], off offset:2048
	global_load_dwordx4 v[190:193], v[14:15], off offset:3072
	v_ashrrev_i32_e32 v9, 31, v8
	v_lshlrev_b64 v[38:39], 11, v[8:9]
	v_add_u32_e32 v4, 0xffffe000, v8
	v_ashrrev_i32_e32 v6, 11, v4
	v_lshlrev_b64 v[4:5], 12, v[8:9]
	v_lshl_add_u64 v[30:31], v[18:19], 0, v[4:5]
	global_load_dwordx4 v[122:125], v[30:31], off
	global_load_dwordx4 v[126:129], v[30:31], off offset:1024
	global_load_dwordx4 v[142:145], v[30:31], off offset:2048
	global_load_dwordx4 v[154:157], v[30:31], off offset:3072
	v_mad_i32_i24 v9, v6, s11, v42
	v_lshl_add_u64 v[6:7], v[12:13], 0, v[38:39]
	global_load_dwordx2 v[114:115], v[6:7], off
	global_load_dwordx2 v[116:117], v[6:7], off offset:512
	global_load_dwordx2 v[118:119], v[6:7], off offset:1024
	global_load_dwordx2 v[120:121], v[6:7], off offset:1536
	v_cmp_lt_i32_e32 vcc, s12, v8
	s_nop 1
	v_cndmask_b32_e32 v32, v43, v9, vcc
	v_ashrrev_i32_e32 v33, 31, v32
	v_lshlrev_b64 v[32:33], 2, v[32:33]
	v_lshl_add_u64 v[62:63], v[20:21], 0, v[32:33]
	global_load_dwordx4 v[130:133], v[62:63], off
	global_load_dwordx4 v[138:141], v[62:63], off offset:1024
	global_load_dwordx4 v[150:153], v[62:63], off offset:2048
	global_load_dwordx4 v[162:165], v[62:63], off offset:3072
	v_lshl_add_u64 v[32:33], s[4:5], 0, v[32:33]
	v_lshl_add_u64 v[96:97], v[32:33], 0, v[10:11]
	global_load_dwordx4 v[202:205], v[96:97], off
	global_load_dwordx4 v[206:209], v[96:97], off offset:1024
	global_load_dwordx4 v[210:213], v[96:97], off offset:2048
	global_load_dwordx4 v[214:217], v[96:97], off offset:3072
	v_lshl_add_u64 v[94:95], v[22:23], 0, v[38:39]
	v_lshl_add_u64 v[38:39], v[32:33], 0, s[8:9]
	v_lshl_add_u64 v[104:105], v[38:39], 0, v[28:29]
	global_load_dwordx4 v[198:201], v[104:105], off
	v_lshl_add_u64 v[102:103], v[38:39], 0, v[26:27]
	global_load_dwordx4 v[186:189], v[102:103], off
	v_lshl_add_u64 v[100:101], v[38:39], 0, v[24:25]
	global_load_dwordx4 v[178:181], v[100:101], off
	v_lshl_add_u64 v[98:99], v[38:39], 0, v[10:11]
	global_load_dwordx4 v[170:173], v[98:99], off
	v_add_u32_e32 v8, s10, v8
	s_waitcnt vmcnt(15)
	v_and_b32_e32 v59, 0xffff0000, v114
	s_waitcnt vmcnt(14)
	v_and_b32_e32 v65, 0xffff0000, v116
	v_lshlrev_b32_e32 v58, 16, v114
	v_lshlrev_b32_e32 v60, 16, v115
	v_and_b32_e32 v61, 0xffff0000, v115
	v_lshlrev_b32_e32 v64, 16, v116
	v_lshlrev_b32_e32 v66, 16, v117
	v_and_b32_e32 v67, 0xffff0000, v117
	s_waitcnt vmcnt(13)
	v_and_b32_e32 v69, 0xffff0000, v118
	s_waitcnt vmcnt(12)
	v_lshlrev_b32_e32 v34, 16, v120
	v_and_b32_e32 v35, 0xffff0000, v120
	v_lshlrev_b32_e32 v36, 16, v121
	v_and_b32_e32 v37, 0xffff0000, v121
	v_mov_b32_e32 v56, v59
	v_mov_b32_e32 v57, v65
	v_lshlrev_b32_e32 v68, 16, v118
	v_lshlrev_b32_e32 v70, 16, v119
	v_and_b32_e32 v71, 0xffff0000, v119
	v_mov_b32_e32 v54, v58
	v_mov_b32_e32 v55, v64
	v_mov_b32_e32 v78, v69
	v_mov_b32_e32 v79, v35
	v_pk_mul_f32 v[56:57], v[56:57], v[56:57]
	v_mov_b32_e32 v72, v60
	v_mov_b32_e32 v73, v66
	v_mov_b32_e32 v76, v68
	v_mov_b32_e32 v77, v34
	v_pk_mul_f32 v[78:79], v[78:79], v[78:79]
	v_pk_fma_f32 v[54:55], v[54:55], v[54:55], v[56:57]
	v_mov_b32_e32 v74, v61
	v_mov_b32_e32 v75, v67
	v_mov_b32_e32 v80, v70
	v_mov_b32_e32 v81, v36
	v_pk_fma_f32 v[56:57], v[76:77], v[76:77], v[78:79]
	v_pk_fma_f32 v[54:55], v[72:73], v[72:73], v[54:55]
	v_mov_b32_e32 v82, v71
	v_mov_b32_e32 v83, v37
	v_pk_fma_f32 v[56:57], v[80:81], v[80:81], v[56:57]
	v_pk_fma_f32 v[54:55], v[74:75], v[74:75], v[54:55]
	v_pk_fma_f32 v[56:57], v[82:83], v[82:83], v[56:57]
	v_add_f32_e32 v9, v54, v55
	v_add_f32_e32 v9, v9, v56
	v_add_f32_e32 v9, v9, v57
	s_nop 1
	s_nop 1
	v_add_f32_dpp v9, v9, v9 quad_perm:[1,0,3,2] row_mask:0xf bank_mask:0xf bound_ctrl:1
	s_nop 1
	s_nop 1
	v_add_f32_dpp v9, v9, v9 quad_perm:[2,3,0,1] row_mask:0xf bank_mask:0xf bound_ctrl:1
	s_nop 1
	s_nop 1
	v_add_f32_dpp v9, v9, v9 row_half_mirror row_mask:0xf bank_mask:0xf bound_ctrl:1
	s_nop 1
	s_nop 1
	v_add_f32_dpp v9, v9, v9 row_mirror row_mask:0xf bank_mask:0xf bound_ctrl:1
	s_nop 1
	ds_bpermute_b32 v45, v40, v9
	s_waitcnt lgkmcnt(0)
	v_add_f32_e32 v9, v9, v45
	s_nop 1
	ds_bpermute_b32 v45, v41, v9
	s_waitcnt lgkmcnt(0)
	v_add_f32_e32 v9, v9, v45
	v_fmamk_f32 v9, v9, 0x3a800000, v44
	v_mul_f32_e32 v45, 0x4b800000, v9
	v_cmp_gt_f32_e32 vcc, s13, v9
	s_nop 1
	s_nop 1
	v_cndmask_b32_e32 v9, v9, v45, vcc
	v_rsq_f32_e32 v9, v9
	s_nop 0
	s_nop 0
	v_mul_f32_e32 v45, 0x45800000, v9
	s_nop 1
	v_cndmask_b32_e32 v72, v9, v45, vcc
	v_pk_mul_f32 v[54:55], v[72:73], v[58:59] op_sel_hi:[0,1]
	v_pk_mul_f32 v[56:57], v[72:73], v[60:61] op_sel_hi:[0,1]
	v_pk_mul_f32 v[0:1], v[110:111], v[54:55]
	v_pk_mul_f32 v[2:3], v[112:113], v[56:57]
	s_waitcnt vmcnt(11)
	v_pk_fma_f32 v[0:1], v[130:131], v[0:1], v[122:123]
	v_pk_fma_f32 v[2:3], v[132:133], v[2:3], v[124:125]
	global_store_dwordx4 v[30:31], v[0:3], off
	s_nop 1
	v_pk_mul_f32 v[58:59], v[72:73], v[64:65] op_sel_hi:[0,1]
	v_pk_mul_f32 v[60:61], v[72:73], v[66:67] op_sel_hi:[0,1]
	v_pk_mul_f32 v[64:65], v[72:73], v[68:69] op_sel_hi:[0,1]
	v_pk_mul_f32 v[66:67], v[72:73], v[70:71] op_sel_hi:[0,1]
	v_mov_b32_e32 v38, v1
	v_pk_mul_f32 v[32:33], v[72:73], v[34:35] op_sel_hi:[0,1]
	v_pk_mul_f32 v[34:35], v[72:73], v[36:37] op_sel_hi:[0,1]
	v_mov_b32_e32 v36, v0
	v_cmp_lt_i32_e32 vcc, s14, v8
	s_or_b64 s[6:7], vcc, s[6:7]
	v_pk_mul_f32 v[4:5], v[58:59], v[134:135]
	v_pk_mul_f32 v[6:7], v[60:61], v[136:137]
	s_waitcnt vmcnt(11)
	v_pk_fma_f32 v[4:5], v[4:5], v[138:139], v[126:127]
	v_pk_fma_f32 v[6:7], v[6:7], v[140:141], v[128:129]
	global_store_dwordx4 v[30:31], v[4:7], off offset:1024
	s_nop 1
	v_mov_b32_e32 v39, v5
	v_mov_b32_e32 v37, v4
	v_pk_mul_f32 v[38:39], v[38:39], v[38:39]
	v_pk_mul_f32 v[46:47], v[64:65], v[146:147]
	v_pk_mul_f32 v[48:49], v[66:67], v[148:149]
	s_waitcnt vmcnt(11)
	v_pk_fma_f32 v[46:47], v[46:47], v[150:151], v[142:143]
	v_pk_fma_f32 v[48:49], v[48:49], v[152:153], v[144:145]
	global_store_dwordx4 v[30:31], v[46:49], off offset:2048
	s_nop 1
	v_mov_b32_e32 v62, v2
	v_mov_b32_e32 v63, v6
	v_pk_fma_f32 v[36:37], v[36:37], v[36:37], v[38:39]
	v_mov_b32_e32 v64, v3
	v_mov_b32_e32 v65, v7
	v_pk_fma_f32 v[36:37], v[62:63], v[62:63], v[36:37]
	v_mov_b32_e32 v108, v47
	v_pk_fma_f32 v[36:37], v[64:65], v[64:65], v[36:37]
	v_mov_b32_e32 v106, v46
	v_add_f32_e32 v9, v36, v37
	v_pk_mul_f32 v[32:33], v[32:33], v[158:159]
	v_pk_mul_f32 v[34:35], v[34:35], v[160:161]
	s_waitcnt vmcnt(11)
	v_pk_fma_f32 v[32:33], v[32:33], v[162:163], v[154:155]
	v_pk_fma_f32 v[34:35], v[34:35], v[164:165], v[156:157]
	global_store_dwordx4 v[30:31], v[32:35], off offset:3072
	s_nop 1
	v_mov_b32_e32 v109, v33
	v_mov_b32_e32 v107, v32
	v_pk_mul_f32 v[98:99], v[108:109], v[108:109]
	v_mov_b32_e32 v30, v48
	v_mov_b32_e32 v31, v34
	v_pk_fma_f32 v[98:99], v[106:107], v[106:107], v[98:99]
	v_mov_b32_e32 v96, v49
	v_mov_b32_e32 v97, v35
	v_pk_fma_f32 v[30:31], v[30:31], v[30:31], v[98:99]
	s_nop 0
	v_pk_fma_f32 v[30:31], v[96:97], v[96:97], v[30:31]
	s_nop 0
	v_add_f32_e32 v9, v9, v30
	v_add_f32_e32 v9, v9, v31
	s_nop 1
	s_nop 1
	v_add_f32_dpp v9, v9, v9 quad_perm:[1,0,3,2] row_mask:0xf bank_mask:0xf bound_ctrl:1
	s_nop 1
	s_nop 1
	v_add_f32_dpp v9, v9, v9 quad_perm:[2,3,0,1] row_mask:0xf bank_mask:0xf bound_ctrl:1
	s_nop 1
	s_nop 1
	v_add_f32_dpp v9, v9, v9 row_half_mirror row_mask:0xf bank_mask:0xf bound_ctrl:1
	s_nop 1
	s_nop 1
	v_add_f32_dpp v9, v9, v9 row_mirror row_mask:0xf bank_mask:0xf bound_ctrl:1
	s_nop 1
	ds_bpermute_b32 v30, v40, v9
	s_waitcnt lgkmcnt(0)
	v_add_f32_e32 v9, v9, v30
	s_nop 1
	ds_bpermute_b32 v30, v41, v9
	s_waitcnt lgkmcnt(0)
	v_add_f32_e32 v9, v9, v30
	v_fmamk_f32 v9, v9, 0x3a800000, v44
	v_mul_f32_e32 v30, 0x4b800000, v9
	v_cmp_gt_f32_e32 vcc, s13, v9
	s_nop 1
	s_nop 1
	v_cndmask_b32_e32 v9, v9, v30, vcc
	v_rsq_f32_e32 v9, v9
	s_nop 0
	s_nop 0
	v_mul_f32_e32 v30, 0x45800000, v9
	s_nop 1
	v_cndmask_b32_e32 v30, v9, v30, vcc
	v_pk_mul_f32 v[0:1], v[0:1], v[30:31] op_sel_hi:[1,0]
	v_pk_mul_f32 v[2:3], v[2:3], v[30:31] op_sel_hi:[1,0]
	v_pk_mul_f32 v[4:5], v[4:5], v[30:31] op_sel_hi:[1,0]
	v_pk_mul_f32 v[6:7], v[6:7], v[30:31] op_sel_hi:[1,0]
	v_pk_mul_f32 v[46:47], v[46:47], v[30:31] op_sel_hi:[1,0]
	v_pk_mul_f32 v[48:49], v[48:49], v[30:31] op_sel_hi:[1,0]
	v_pk_mul_f32 v[32:33], v[32:33], v[30:31] op_sel_hi:[1,0]
	v_pk_mul_f32 v[30:31], v[34:35], v[30:31] op_sel_hi:[1,0]
	v_pk_mul_f32 v[0:1], v[166:167], v[0:1]
	s_waitcnt vmcnt(4)
	v_pk_add_f32 v[34:35], v[170:171], 1.0 op_sel_hi:[1,0]
	v_pk_mul_f32 v[2:3], v[168:169], v[2:3]
	v_pk_add_f32 v[36:37], v[172:173], 1.0 op_sel_hi:[1,0]
	v_pk_mul_f32 v[4:5], v[4:5], v[174:175]
	v_pk_add_f32 v[38:39], v[178:179], 1.0 op_sel_hi:[1,0]
	v_pk_mul_f32 v[6:7], v[6:7], v[176:177]
	v_pk_add_f32 v[50:51], v[180:181], 1.0 op_sel_hi:[1,0]
	v_pk_mul_f32 v[46:47], v[46:47], v[182:183]
	v_pk_add_f32 v[52:53], v[186:187], 1.0 op_sel_hi:[1,0]
	v_pk_mul_f32 v[48:49], v[48:49], v[184:185]
	v_pk_add_f32 v[54:55], v[188:189], 1.0 op_sel_hi:[1,0]
	v_pk_mul_f32 v[32:33], v[32:33], v[190:191]
	v_pk_add_f32 v[56:57], v[198:199], 1.0 op_sel_hi:[1,0]
	v_pk_mul_f32 v[30:31], v[30:31], v[192:193]
	v_pk_add_f32 v[58:59], v[200:201], 1.0 op_sel_hi:[1,0]
	v_pk_fma_f32 v[0:1], v[0:1], v[34:35], v[202:203]
	v_pk_fma_f32 v[2:3], v[2:3], v[36:37], v[204:205]
	v_pk_fma_f32 v[4:5], v[4:5], v[38:39], v[206:207]
	v_pk_fma_f32 v[6:7], v[6:7], v[50:51], v[208:209]
	v_pk_fma_f32 v[34:35], v[46:47], v[52:53], v[210:211]
	v_pk_fma_f32 v[36:37], v[48:49], v[54:55], v[212:213]
	v_pk_fma_f32 v[32:33], v[32:33], v[56:57], v[214:215]
	v_pk_fma_f32 v[30:31], v[30:31], v[58:59], v[216:217]
	v_cvt_pk_bf16_f32 v0, v0, v1
	v_cvt_pk_bf16_f32 v1, v2, v3
	v_cvt_pk_bf16_f32 v2, v4, v5
	v_cvt_pk_bf16_f32 v3, v6, v7
	v_cvt_pk_bf16_f32 v4, v34, v35
	v_cvt_pk_bf16_f32 v5, v36, v37
	v_cvt_pk_bf16_f32 v6, v32, v33
	v_cvt_pk_bf16_f32 v7, v30, v31
	global_store_dwordx2 v[94:95], v[0:1], off
	s_nop 1
	global_store_dwordx2 v[94:95], v[2:3], off offset:512
	s_nop 1
	global_store_dwordx2 v[94:95], v[4:5], off offset:1024
	s_nop 1
	global_store_dwordx2 v[94:95], v[6:7], off offset:1536
	s_nop 1
	s_andn2_b64 exec, exec, s[6:7]
	s_cbranch_execnz .LBB0_1834

.LBB0_2106:
	global_load_dwordx4 v[118:121], v[4:5], off
	global_load_dwordx4 v[134:137], v[4:5], off offset:1024
	global_load_dwordx4 v[146:149], v[4:5], off offset:2048
	global_load_dwordx4 v[158:161], v[4:5], off offset:3072
	v_ashrrev_i32_e32 v1, 31, v0
	v_lshlrev_b64 v[20:21], 12, v[0:1]
	v_lshl_add_u64 v[40:41], v[6:7], 0, v[20:21]
	global_load_dwordx4 v[122:125], v[40:41], off
	global_load_dwordx4 v[126:129], v[40:41], off offset:1024
	global_load_dwordx4 v[142:145], v[40:41], off offset:2048
	global_load_dwordx4 v[154:157], v[40:41], off offset:3072
	v_lshlrev_b64 v[16:17], 11, v[0:1]
	v_lshl_add_u64 v[16:17], v[2:3], 0, v[16:17]
	global_load_dwordx2 v[110:111], v[16:17], off
	global_load_dwordx2 v[112:113], v[16:17], off offset:512
	global_load_dwordx2 v[114:115], v[16:17], off offset:1024
	global_load_dwordx2 v[116:117], v[16:17], off offset:1536
	v_add_u32_e32 v15, 0xffffe000, v0
	v_ashrrev_i32_e32 v15, 11, v15
	v_mad_i32_i24 v1, v15, s3, v12
	v_cmp_lt_i32_e32 vcc, s4, v0
	s_nop 1
	v_cndmask_b32_e32 v28, v13, v1, vcc
	v_ashrrev_i32_e32 v29, 31, v28
	v_lshl_add_u64 v[42:43], v[28:29], 2, v[8:9]
	global_load_dwordx4 v[130:133], v[42:43], off
	global_load_dwordx4 v[138:141], v[42:43], off offset:1024
	global_load_dwordx4 v[150:153], v[42:43], off offset:2048
	global_load_dwordx4 v[162:165], v[42:43], off offset:3072
	v_add_u32_e32 v0, s2, v0
	s_waitcnt vmcnt(7)
	v_and_b32_e32 v45, 0xffff0000, v110
	s_waitcnt vmcnt(6)
	v_and_b32_e32 v47, 0xffff0000, v112
	v_lshlrev_b32_e32 v44, 16, v110
	v_lshlrev_b32_e32 v46, 16, v112
	s_waitcnt vmcnt(5)
	v_and_b32_e32 v49, 0xffff0000, v114
	s_waitcnt vmcnt(4)
	v_and_b32_e32 v51, 0xffff0000, v116
	v_mov_b32_e32 v54, v45
	v_mov_b32_e32 v55, v47
	v_lshlrev_b32_e32 v32, 16, v111
	v_lshlrev_b32_e32 v34, 16, v113
	v_lshlrev_b32_e32 v48, 16, v114
	v_lshlrev_b32_e32 v50, 16, v116
	v_mov_b32_e32 v52, v44
	v_mov_b32_e32 v53, v46
	v_mov_b32_e32 v62, v49
	v_mov_b32_e32 v63, v51
	v_pk_mul_f32 v[54:55], v[54:55], v[54:55]
	v_and_b32_e32 v33, 0xffff0000, v111
	v_and_b32_e32 v35, 0xffff0000, v113
	v_lshlrev_b32_e32 v36, 16, v115
	v_lshlrev_b32_e32 v38, 16, v117
	v_mov_b32_e32 v56, v32
	v_mov_b32_e32 v57, v34
	v_mov_b32_e32 v60, v48
	v_mov_b32_e32 v61, v50
	v_pk_mul_f32 v[62:63], v[62:63], v[62:63]
	v_pk_fma_f32 v[52:53], v[52:53], v[52:53], v[54:55]
	v_and_b32_e32 v37, 0xffff0000, v115
	v_and_b32_e32 v39, 0xffff0000, v117
	v_mov_b32_e32 v58, v33
	v_mov_b32_e32 v59, v35
	v_mov_b32_e32 v64, v36
	v_mov_b32_e32 v65, v38
	v_pk_fma_f32 v[54:55], v[60:61], v[60:61], v[62:63]
	v_pk_fma_f32 v[52:53], v[56:57], v[56:57], v[52:53]
	v_mov_b32_e32 v66, v37
	v_mov_b32_e32 v67, v39
	v_pk_fma_f32 v[54:55], v[64:65], v[64:65], v[54:55]
	v_pk_fma_f32 v[52:53], v[58:59], v[58:59], v[52:53]
	v_pk_fma_f32 v[54:55], v[66:67], v[66:67], v[54:55]
	v_add_f32_e32 v1, v52, v53
	v_add_f32_e32 v1, v1, v54
	v_add_f32_e32 v1, v1, v55
	s_nop 1
	s_nop 1
	v_add_f32_dpp v1, v1, v1 quad_perm:[1,0,3,2] row_mask:0xf bank_mask:0xf bound_ctrl:1
	s_nop 1
	s_nop 1
	v_add_f32_dpp v1, v1, v1 quad_perm:[2,3,0,1] row_mask:0xf bank_mask:0xf bound_ctrl:1
	s_nop 1
	s_nop 1
	v_add_f32_dpp v1, v1, v1 row_half_mirror row_mask:0xf bank_mask:0xf bound_ctrl:1
	s_nop 1
	s_nop 1
	v_add_f32_dpp v1, v1, v1 row_mirror row_mask:0xf bank_mask:0xf bound_ctrl:1
	s_nop 1
	ds_bpermute_b32 v15, v10, v1
	s_waitcnt lgkmcnt(0)
	v_add_f32_e32 v1, v1, v15
	s_nop 1
	ds_bpermute_b32 v15, v11, v1
	s_waitcnt lgkmcnt(0)
	v_add_f32_e32 v1, v1, v15
	v_fmamk_f32 v1, v1, 0x3a800000, v14
	v_mul_f32_e32 v15, 0x4b800000, v1
	v_cmp_gt_f32_e32 vcc, s5, v1
	s_nop 1
	s_nop 1
	v_cndmask_b32_e32 v1, v1, v15, vcc
	v_rsq_f32_e32 v1, v1
	s_nop 0
	s_nop 0
	v_mul_f32_e32 v15, 0x45800000, v1
	s_nop 1
	v_cndmask_b32_e32 v52, v1, v15, vcc
	v_pk_mul_f32 v[44:45], v[52:53], v[44:45] op_sel_hi:[0,1]
	v_pk_mul_f32 v[32:33], v[52:53], v[32:33] op_sel_hi:[0,1]
	v_pk_mul_f32 v[16:17], v[118:119], v[44:45]
	v_pk_mul_f32 v[18:19], v[120:121], v[32:33]
	s_waitcnt vmcnt(3)
	v_pk_fma_f32 v[16:17], v[130:131], v[16:17], v[122:123]
	v_pk_fma_f32 v[18:19], v[132:133], v[18:19], v[124:125]
	global_store_dwordx4 v[40:41], v[16:19], off
	s_nop 1
	s_nop 0
	v_pk_mul_f32 v[32:33], v[52:53], v[46:47] op_sel_hi:[0,1]
	v_pk_mul_f32 v[34:35], v[52:53], v[34:35] op_sel_hi:[0,1]
	v_cmp_lt_i32_e32 vcc, s6, v0
	s_or_b64 s[0:1], vcc, s[0:1]
	v_pk_mul_f32 v[16:17], v[32:33], v[134:135]
	v_pk_mul_f32 v[18:19], v[34:35], v[136:137]
	s_waitcnt vmcnt(3)
	v_pk_fma_f32 v[16:17], v[16:17], v[138:139], v[126:127]
	v_pk_fma_f32 v[18:19], v[18:19], v[140:141], v[128:129]
	global_store_dwordx4 v[40:41], v[16:19], off offset:1024
	s_nop 1
	s_nop 0
	v_pk_mul_f32 v[32:33], v[52:53], v[48:49] op_sel_hi:[0,1]
	v_pk_mul_f32 v[34:35], v[52:53], v[36:37] op_sel_hi:[0,1]
	v_pk_mul_f32 v[16:17], v[32:33], v[146:147]
	v_pk_mul_f32 v[18:19], v[34:35], v[148:149]
	s_waitcnt vmcnt(3)
	v_pk_fma_f32 v[16:17], v[16:17], v[150:151], v[142:143]
	v_pk_fma_f32 v[18:19], v[18:19], v[152:153], v[144:145]
	global_store_dwordx4 v[40:41], v[16:19], off offset:2048
	s_nop 1
	s_nop 0
	v_pk_mul_f32 v[28:29], v[52:53], v[50:51] op_sel_hi:[0,1]
	v_pk_mul_f32 v[30:31], v[52:53], v[38:39] op_sel_hi:[0,1]
	v_pk_mul_f32 v[16:17], v[28:29], v[158:159]
	v_pk_mul_f32 v[18:19], v[30:31], v[160:161]
	s_waitcnt vmcnt(3)
	v_pk_fma_f32 v[16:17], v[16:17], v[162:163], v[154:155]
	v_pk_fma_f32 v[18:19], v[18:19], v[164:165], v[156:157]
	global_store_dwordx4 v[40:41], v[16:19], off offset:3072
	s_nop 1
	s_andn2_b64 exec, exec, s[0:1]
	s_cbranch_execnz .LBB0_2106
